# P0 item: 16 dwordx4 row loads (4 rows per instruction) instead of 64 dword loads
# speedup vs baseline: 1.0111x; 1.0074x over previous
; #define LAS __attribute__((address_space(3)))
; __global__ void __launch_bounds__(NWAVES * 64, 2) fwd_megakernel(Args args) {
;     ...
;     bf16_t* W1 = (bf16_t*)(ws + WS_W1); bf16_t* WD1 = (bf16_t*)(ws + WS_WD1); bf16_t* VT = (bf16_t*)(ws + WS_VT);
;     bf16_t* WQK = (bf16_t*)(ws + WS_WQK); bf16_t* WV = (bf16_t*)(ws + WS_WV); bf16_t* WO = (bf16_t*)(ws + WS_WO);
;     bf16_t* W2 = (bf16_t*)(ws + WS_W2); bf16_t* WD2 = (bf16_t*)(ws + WS_WD2); bf16_t* WPG = (bf16_t*)(ws + WS_WPG); bf16_t* WPP = (bf16_t*)(ws + WS_WPP);
;     bf16_t* PB = (bf16_t*)(ws + WS_PB); bf16_t* XB = (bf16_t*)(ws + WS_XB); bf16_t* HB = (bf16_t*)(ws + WS_H); bf16_t* QKB = (bf16_t*)(ws + WS_QK); bf16_t* CAT = (bf16_t*)(ws + WS_CAT);
;     {
;         LAS float* scr = (LAS float*)(lds + wave * 16640);
;         constexpr int I_GU = (DM / 64) * (FF / 64), I_DN = (FF / 64) * (DM / 64), I_IN = (DM / 64) * (1024 / 64), I_SQ = (DM / 64) * (DM / 64), I_PP = (PLE / 64) * (DM / 64);
;         constexpr int NITEMS = 4 * I_GU + 2 * I_DN + 6 * I_IN + 2 * I_SQ + I_PP;
;         for (int it = gw; it < NITEMS; it += NGW) {
.LBB0_28:
	v_writelane_b32 v250, s30, 30
	s_nop 1
	v_writelane_b32 v250, s31, 31
	v_writelane_b32 v250, s27, 32
	s_or_b64 exec, exec, s[4:5]
	s_lshr_b32 s64, s3, 6
	s_lshl_b32 s1, s26, 3
	s_add_i32 s1, s1, s64
	s_add_u32 s4, s60, 0x200000
	s_addc_u32 s5, s61, 0
	v_writelane_b32 v250, s4, 34
	v_and_b32_e32 v168, 63, v166
	s_nop 0
	v_writelane_b32 v250, s5, 35
	s_add_u32 s4, s60, 0x2e00000
	s_addc_u32 s5, s61, 0
	v_writelane_b32 v250, s4, 36
	s_nop 1
	v_writelane_b32 v250, s5, 37
	s_add_u32 s4, s60, 0x4400000
	s_addc_u32 s5, s61, 0
	v_writelane_b32 v250, s4, 38
	s_nop 1
	v_writelane_b32 v250, s5, 39
	s_add_u32 s4, s60, 0x5400000
	s_addc_u32 s5, s61, 0
	v_writelane_b32 v250, s4, 40
	s_nop 1
	v_writelane_b32 v250, s5, 41
	s_add_u32 s4, s60, 0x5c00000
	s_addc_u32 s5, s61, 0
	v_writelane_b32 v250, s4, 42
	s_nop 1
	v_writelane_b32 v250, s5, 43
	s_add_u32 s4, s60, 0x6400000
	s_addc_u32 s5, s61, 0
	v_writelane_b32 v250, s4, 44
	s_nop 1
	v_writelane_b32 v250, s5, 45
	s_add_u32 s4, s60, 0x9000000
	s_addc_u32 s5, s61, 0
	v_writelane_b32 v250, s4, 46
	s_nop 1
	v_writelane_b32 v250, s5, 47
	s_add_u32 s4, s60, 0xa600000
	s_addc_u32 s5, s61, 0
	v_writelane_b32 v250, s4, 48
	s_nop 1
	v_writelane_b32 v250, s5, 49
	s_add_u32 s4, s60, 0xae00000
	s_addc_u32 s5, s61, 0
	v_writelane_b32 v250, s4, 50
	s_cmpk_gt_i32 s1, 0x567f
	s_nop 0
	v_writelane_b32 v250, s5, 51
	v_writelane_b32 v250, s1, 52
	s_cbranch_scc1 .LBB0_120
	v_lshlrev_b32_e32 v66, 2, v168
	v_and_b32_e32 v0, 7, v168
	v_lshlrev_b32_e32 v67, 5, v0
	v_lshrrev_b32_e32 v79, 3, v168
	s_mul_i32 s3, s64, 0x4100
	v_mul_u32_u24_e32 v77, 0x820, v0
	v_lshl_add_u32 v77, v79, 2, v77
	v_add_u32_e32 v77, s3, v77
	v_lshlrev_b32_e32 v92, 4, v0
	v_lshrrev_b32_e32 v93, 4, v168
	v_and_b32_e32 v94, 15, v168
	v_lshlrev_b32_e32 v94, 4, v94
	v_mul_u32_u24_e32 v95, 0x104, v93
	v_add3_u32 v76, v95, v94, s3
	v_readlane_b32 s55, v250, 52
	s_lshl_b32 s1, s62, 3

; __device__ __forceinline__ void p0_item(const float* W, int ldw, int col0, int k0, const float* gain, bf16_t* WT, int K, int drow0, LAS float* scr, int lane) {
;     ...
;     const float* src = W + (size_t)k0 * ldw + col0 + lane;
; #pragma unroll
;     for (int i = 0; i < 64; ++i) v[i] = src[(size_t)i * ldw];
;     const int c = lane & 7;
;     f32x4 g0 = {1.f, 1.f, 1.f, 1.f}, g1 = {1.f, 1.f, 1.f, 1.f};
;     if (gain) { g0 = *(const f32x4*)(gain + k0 + 8 * c); g1 = *(const f32x4*)(gain + k0 + 8 * c + 4); }
; #pragma unroll
;     for (int i = 0; i < 64; ++i) scr[i * 65 + lane] = v[i];
.Lp0_rows:
	s_mul_i32 s4, s33, s30
	s_add_u32 s4, s4, s31
	s_lshl_b32 s4, s4, 2
	s_add_u32 s40, s28, s4
	s_addc_u32 s41, s29, 0
	s_lshl_b32 s5, s30, 2
	v_mul_lo_u32 v66, v93, s5
	v_add_u32_e32 v66, v66, v94
	s_lshl_b32 s5, s5, 2
	global_load_dwordx4 v[2:5], v66, s[40:41]
	s_add_u32 s40, s40, s5
	s_addc_u32 s41, s41, 0
	global_load_dwordx4 v[6:9], v66, s[40:41]
	s_add_u32 s40, s40, s5
	s_addc_u32 s41, s41, 0
	global_load_dwordx4 v[10:13], v66, s[40:41]
	s_add_u32 s40, s40, s5
	s_addc_u32 s41, s41, 0
	global_load_dwordx4 v[14:17], v66, s[40:41]
	s_add_u32 s40, s40, s5
	s_addc_u32 s41, s41, 0
	global_load_dwordx4 v[18:21], v66, s[40:41]
	s_add_u32 s40, s40, s5
	s_addc_u32 s41, s41, 0
	global_load_dwordx4 v[22:25], v66, s[40:41]
	s_add_u32 s40, s40, s5
	s_addc_u32 s41, s41, 0
	global_load_dwordx4 v[26:29], v66, s[40:41]
	s_add_u32 s40, s40, s5
	s_addc_u32 s41, s41, 0
	global_load_dwordx4 v[30:33], v66, s[40:41]
	s_add_u32 s40, s40, s5
	s_addc_u32 s41, s41, 0
	global_load_dwordx4 v[34:37], v66, s[40:41]
	s_add_u32 s40, s40, s5
	s_addc_u32 s41, s41, 0
	global_load_dwordx4 v[38:41], v66, s[40:41]
	s_add_u32 s40, s40, s5
	s_addc_u32 s41, s41, 0
	global_load_dwordx4 v[42:45], v66, s[40:41]
	s_add_u32 s40, s40, s5
	s_addc_u32 s41, s41, 0
	global_load_dwordx4 v[46:49], v66, s[40:41]
	s_add_u32 s40, s40, s5
	s_addc_u32 s41, s41, 0
	global_load_dwordx4 v[50:53], v66, s[40:41]
	s_add_u32 s40, s40, s5
	s_addc_u32 s41, s41, 0
	global_load_dwordx4 v[54:57], v66, s[40:41]
	s_add_u32 s40, s40, s5
	s_addc_u32 s41, s41, 0
	global_load_dwordx4 v[58:61], v66, s[40:41]
	s_add_u32 s40, s40, s5
	s_addc_u32 s41, s41, 0
	global_load_dwordx4 v[62:65], v66, s[40:41]
	s_mul_i32 s4, s39, s38
	s_add_u32 s4, s4, s33
	s_lshl_b32 s4, s4, 1
	s_add_u32 s44, s36, s4
	s_addc_u32 s45, s37, 0
	s_lshl_b32 s6, s38, 1
	v_mul_lo_u32 v78, v79, s6
	v_add_u32_e32 v78, v78, v92
	s_lshl_b32 s46, s38, 4
	s_waitcnt vmcnt(15)
	ds_write_b32 v76, v2 offset:0
	ds_write_b32 v76, v3 offset:4
	ds_write_b32 v76, v4 offset:8
	ds_write_b32 v76, v5 offset:12
	s_waitcnt vmcnt(14)
	ds_write_b32 v76, v6 offset:1040
	ds_write_b32 v76, v7 offset:1044
	ds_write_b32 v76, v8 offset:1048
	ds_write_b32 v76, v9 offset:1052
	s_waitcnt vmcnt(13)
	ds_write_b32 v76, v10 offset:2080
	ds_write_b32 v76, v11 offset:2084
	ds_write_b32 v76, v12 offset:2088
	ds_write_b32 v76, v13 offset:2092
	s_waitcnt vmcnt(12)
	ds_write_b32 v76, v14 offset:3120
	ds_write_b32 v76, v15 offset:3124
	ds_write_b32 v76, v16 offset:3128
	ds_write_b32 v76, v17 offset:3132
	s_waitcnt vmcnt(11)
	ds_write_b32 v76, v18 offset:4160
	ds_write_b32 v76, v19 offset:4164
	ds_write_b32 v76, v20 offset:4168
	ds_write_b32 v76, v21 offset:4172
	s_waitcnt vmcnt(10)
	ds_write_b32 v76, v22 offset:5200
	ds_write_b32 v76, v23 offset:5204
	ds_write_b32 v76, v24 offset:5208
	ds_write_b32 v76, v25 offset:5212
	s_waitcnt vmcnt(9)
	ds_write_b32 v76, v26 offset:6240
	ds_write_b32 v76, v27 offset:6244
	ds_write_b32 v76, v28 offset:6248
	ds_write_b32 v76, v29 offset:6252
	s_waitcnt vmcnt(8)
	ds_write_b32 v76, v30 offset:7280
	ds_write_b32 v76, v31 offset:7284
	ds_write_b32 v76, v32 offset:7288
	ds_write_b32 v76, v33 offset:7292
	s_waitcnt vmcnt(7)
	ds_write_b32 v76, v34 offset:8320
	ds_write_b32 v76, v35 offset:8324
	ds_write_b32 v76, v36 offset:8328
	ds_write_b32 v76, v37 offset:8332
	s_waitcnt vmcnt(6)
	ds_write_b32 v76, v38 offset:9360
	ds_write_b32 v76, v39 offset:9364
	ds_write_b32 v76, v40 offset:9368
	ds_write_b32 v76, v41 offset:9372
	s_waitcnt vmcnt(5)
	ds_write_b32 v76, v42 offset:10400
	ds_write_b32 v76, v43 offset:10404
	ds_write_b32 v76, v44 offset:10408
	ds_write_b32 v76, v45 offset:10412
	s_waitcnt vmcnt(4)
	ds_write_b32 v76, v46 offset:11440
	ds_write_b32 v76, v47 offset:11444
	ds_write_b32 v76, v48 offset:11448
	ds_write_b32 v76, v49 offset:11452
	s_waitcnt vmcnt(3)
	ds_write_b32 v76, v50 offset:12480
	ds_write_b32 v76, v51 offset:12484
	ds_write_b32 v76, v52 offset:12488
	ds_write_b32 v76, v53 offset:12492
	s_waitcnt vmcnt(2)
	ds_write_b32 v76, v54 offset:13520
	ds_write_b32 v76, v55 offset:13524
	ds_write_b32 v76, v56 offset:13528
	ds_write_b32 v76, v57 offset:13532
	s_waitcnt vmcnt(1)
	ds_write_b32 v76, v58 offset:14560
	ds_write_b32 v76, v59 offset:14564
	ds_write_b32 v76, v60 offset:14568
	ds_write_b32 v76, v61 offset:14572
	s_waitcnt vmcnt(0)
	ds_write_b32 v76, v62 offset:15600
	ds_write_b32 v76, v63 offset:15604
	ds_write_b32 v76, v64 offset:15608
	ds_write_b32 v76, v65 offset:15612
	s_waitcnt lgkmcnt(0)
	ds_read_b32 v80, v77 offset:0
	ds_read_b32 v81, v77 offset:260
	ds_read_b32 v82, v77 offset:520
	ds_read_b32 v83, v77 offset:780
	ds_read_b32 v84, v77 offset:1040
	ds_read_b32 v85, v77 offset:1300
	ds_read_b32 v86, v77 offset:1560
	ds_read_b32 v87, v77 offset:1820
	s_waitcnt lgkmcnt(0)
; #define LAS __attribute__((address_space(3)))
; __device__ __forceinline__ unsigned cvtpk(float lo, float hi) { f32x2 v = {lo, hi}; bf16x2_t b = __builtin_convertvector(v, bf16x2_t); return __builtin_bit_cast(unsigned, b); }
; __device__ __forceinline__ void p0_item(const float* W, int ldw, int col0, int k0, const float* gain, bf16_t* WT, int K, int drow0, LAS float* scr, int lane) {
;     ...
;     for (int j = 0; j < 8; ++j) { const int n = (lane >> 3) + 8 * j; const LAS float* s = scr + (8 * c) * 65 + n;
;         u32x4 o; o.x = cvtpk(s[0 * 65] * g0[0], s[1 * 65] * g0[1]); o.y = cvtpk(s[2 * 65] * g0[2], s[3 * 65] * g0[3]); o.z = cvtpk(s[4 * 65] * g1[0], s[5 * 65] * g1[1]); o.w = cvtpk(s[6 * 65] * g1[2], s[7 * 65] * g1[3]);
;         *(u32x4*)(WT + (size_t)(drow0 + n) * K + k0 + 8 * c) = o; }
;     asm volatile("s_waitcnt lgkmcnt(0)" ::: "memory");
	v_pk_mul_f32 v[84:85], v[84:85], v[72:73]
	v_pk_mul_f32 v[86:87], v[86:87], v[74:75]
	v_pk_mul_f32 v[80:81], v[80:81], v[68:69]
	v_pk_mul_f32 v[82:83], v[82:83], v[70:71]
	v_cvt_pk_bf16_f32 v90, v84, v85
	v_cvt_pk_bf16_f32 v91, v86, v87
	v_cvt_pk_bf16_f32 v88, v80, v81
	v_cvt_pk_bf16_f32 v89, v82, v83
	ds_read_b32 v80, v77 offset:32
	ds_read_b32 v81, v77 offset:292
	ds_read_b32 v82, v77 offset:552
	ds_read_b32 v83, v77 offset:812
	ds_read_b32 v84, v77 offset:1072
	ds_read_b32 v85, v77 offset:1332
	ds_read_b32 v86, v77 offset:1592
	ds_read_b32 v87, v77 offset:1852
	global_store_dwordx4 v78, v[88:91], s[44:45]
	s_add_u32 s44, s44, s46
	s_addc_u32 s45, s45, 0
	s_waitcnt lgkmcnt(0)
	v_pk_mul_f32 v[84:85], v[84:85], v[72:73]
	v_pk_mul_f32 v[86:87], v[86:87], v[74:75]
	v_pk_mul_f32 v[80:81], v[80:81], v[68:69]
	v_pk_mul_f32 v[82:83], v[82:83], v[70:71]
	v_cvt_pk_bf16_f32 v90, v84, v85
	v_cvt_pk_bf16_f32 v91, v86, v87
	v_cvt_pk_bf16_f32 v88, v80, v81
	v_cvt_pk_bf16_f32 v89, v82, v83
	ds_read_b32 v80, v77 offset:64
	ds_read_b32 v81, v77 offset:324
	ds_read_b32 v82, v77 offset:584
	ds_read_b32 v83, v77 offset:844
	ds_read_b32 v84, v77 offset:1104
	ds_read_b32 v85, v77 offset:1364
	ds_read_b32 v86, v77 offset:1624
	ds_read_b32 v87, v77 offset:1884
	global_store_dwordx4 v78, v[88:91], s[44:45]
	s_add_u32 s44, s44, s46
	s_addc_u32 s45, s45, 0
	s_waitcnt lgkmcnt(0)
	v_pk_mul_f32 v[84:85], v[84:85], v[72:73]
	v_pk_mul_f32 v[86:87], v[86:87], v[74:75]
	v_pk_mul_f32 v[80:81], v[80:81], v[68:69]
	v_pk_mul_f32 v[82:83], v[82:83], v[70:71]
	v_cvt_pk_bf16_f32 v90, v84, v85
	v_cvt_pk_bf16_f32 v91, v86, v87
	v_cvt_pk_bf16_f32 v88, v80, v81
	v_cvt_pk_bf16_f32 v89, v82, v83
	ds_read_b32 v80, v77 offset:96
	ds_read_b32 v81, v77 offset:356
	ds_read_b32 v82, v77 offset:616
	ds_read_b32 v83, v77 offset:876
	ds_read_b32 v84, v77 offset:1136
	ds_read_b32 v85, v77 offset:1396
	ds_read_b32 v86, v77 offset:1656
	ds_read_b32 v87, v77 offset:1916
	global_store_dwordx4 v78, v[88:91], s[44:45]
	s_add_u32 s44, s44, s46
	s_addc_u32 s45, s45, 0
	s_waitcnt lgkmcnt(0)
	v_pk_mul_f32 v[84:85], v[84:85], v[72:73]
	v_pk_mul_f32 v[86:87], v[86:87], v[74:75]
	v_pk_mul_f32 v[80:81], v[80:81], v[68:69]
	v_pk_mul_f32 v[82:83], v[82:83], v[70:71]
	v_cvt_pk_bf16_f32 v90, v84, v85
	v_cvt_pk_bf16_f32 v91, v86, v87
	v_cvt_pk_bf16_f32 v88, v80, v81
	v_cvt_pk_bf16_f32 v89, v82, v83
	ds_read_b32 v80, v77 offset:128
	ds_read_b32 v81, v77 offset:388
	ds_read_b32 v82, v77 offset:648
	ds_read_b32 v83, v77 offset:908
	ds_read_b32 v84, v77 offset:1168
	ds_read_b32 v85, v77 offset:1428
	ds_read_b32 v86, v77 offset:1688
	ds_read_b32 v87, v77 offset:1948
	global_store_dwordx4 v78, v[88:91], s[44:45]
	s_add_u32 s44, s44, s46
	s_addc_u32 s45, s45, 0
	s_waitcnt lgkmcnt(0)
	v_pk_mul_f32 v[84:85], v[84:85], v[72:73]
	v_pk_mul_f32 v[86:87], v[86:87], v[74:75]
	v_pk_mul_f32 v[80:81], v[80:81], v[68:69]
	v_pk_mul_f32 v[82:83], v[82:83], v[70:71]
	v_cvt_pk_bf16_f32 v90, v84, v85
	v_cvt_pk_bf16_f32 v91, v86, v87
	v_cvt_pk_bf16_f32 v88, v80, v81
	v_cvt_pk_bf16_f32 v89, v82, v83
	ds_read_b32 v80, v77 offset:160
	ds_read_b32 v81, v77 offset:420
	ds_read_b32 v82, v77 offset:680
	ds_read_b32 v83, v77 offset:940
	ds_read_b32 v84, v77 offset:1200
	ds_read_b32 v85, v77 offset:1460
	ds_read_b32 v86, v77 offset:1720
	ds_read_b32 v87, v77 offset:1980
	global_store_dwordx4 v78, v[88:91], s[44:45]
	s_add_u32 s44, s44, s46
	s_addc_u32 s45, s45, 0
	s_waitcnt lgkmcnt(0)
	v_pk_mul_f32 v[84:85], v[84:85], v[72:73]
	v_pk_mul_f32 v[86:87], v[86:87], v[74:75]
	v_pk_mul_f32 v[80:81], v[80:81], v[68:69]
	v_pk_mul_f32 v[82:83], v[82:83], v[70:71]
	v_cvt_pk_bf16_f32 v90, v84, v85
	v_cvt_pk_bf16_f32 v91, v86, v87
	v_cvt_pk_bf16_f32 v88, v80, v81
	v_cvt_pk_bf16_f32 v89, v82, v83
	ds_read_b32 v80, v77 offset:192
	ds_read_b32 v81, v77 offset:452
	ds_read_b32 v82, v77 offset:712
	ds_read_b32 v83, v77 offset:972
	ds_read_b32 v84, v77 offset:1232
	ds_read_b32 v85, v77 offset:1492
	ds_read_b32 v86, v77 offset:1752
	ds_read_b32 v87, v77 offset:2012
	global_store_dwordx4 v78, v[88:91], s[44:45]
	s_add_u32 s44, s44, s46
	s_addc_u32 s45, s45, 0
	s_waitcnt lgkmcnt(0)
	v_pk_mul_f32 v[84:85], v[84:85], v[72:73]
	v_pk_mul_f32 v[86:87], v[86:87], v[74:75]
	v_pk_mul_f32 v[80:81], v[80:81], v[68:69]
	v_pk_mul_f32 v[82:83], v[82:83], v[70:71]
	v_cvt_pk_bf16_f32 v90, v84, v85
	v_cvt_pk_bf16_f32 v91, v86, v87
	v_cvt_pk_bf16_f32 v88, v80, v81
	v_cvt_pk_bf16_f32 v89, v82, v83
	ds_read_b32 v80, v77 offset:224
	ds_read_b32 v81, v77 offset:484
	ds_read_b32 v82, v77 offset:744
	ds_read_b32 v83, v77 offset:1004
	ds_read_b32 v84, v77 offset:1264
	ds_read_b32 v85, v77 offset:1524
	ds_read_b32 v86, v77 offset:1784
	ds_read_b32 v87, v77 offset:2044
	global_store_dwordx4 v78, v[88:91], s[44:45]
	s_add_u32 s44, s44, s46
	s_addc_u32 s45, s45, 0
	s_waitcnt lgkmcnt(0)
	v_pk_mul_f32 v[84:85], v[84:85], v[72:73]
	v_pk_mul_f32 v[86:87], v[86:87], v[74:75]
	v_pk_mul_f32 v[80:81], v[80:81], v[68:69]
	v_pk_mul_f32 v[82:83], v[82:83], v[70:71]
	v_cvt_pk_bf16_f32 v90, v84, v85
	v_cvt_pk_bf16_f32 v91, v86, v87
	v_cvt_pk_bf16_f32 v88, v80, v81
	v_cvt_pk_bf16_f32 v89, v82, v83
	global_store_dwordx4 v78, v[88:91], s[44:45]
	s_add_i32 s55, s55, s1
	s_cmpk_gt_i32 s55, 0x567f
	s_cbranch_scc0 .Lp0_loop
